# perm + seam after ph5 XCD-local (post/check event) + ret_out decay factors without exp2f's unreachable underflow-rescue path
# speedup vs baseline: 1.0073x; 1.0036x over previous
; #define LAS __attribute__((address_space(3)))
; __device__ __forceinline__ void ret_out_phase(const Frame& F, const bf16* P0, const bf16* RT, bf16* MIX) {
;     ...
; #pragma unroll
;         for (int et = 0; et < 4; ++et) { const LAS bf16* rp = Rs + (16 * et + fr) * QK_LD + 8 * fq; const bf16x8 r0 = *(const LAS bf16x8*)rp, r1 = *(const LAS bf16x8*)(rp + 32);
;             ai[et] = __builtin_amdgcn_mfma_f32_16x16x32_bf16(r0, q0, ai[et], 0, 0, 0); ai[et] = __builtin_amdgcn_mfma_f32_16x16x32_bf16(r1, q1, ai[et], 0, 0, 0); }
;         const float xi = exp2f((float)(t + 1) * lg);
;         float sum = 0.f;
; #pragma unroll
;         for (int et = 0; et < 4; ++et) { ao[et] = ao[et] + ai[et] * xi; sum += (ao[et][0] + ao[et][1]) + (ao[et][2] + ao[et][3]); }
;         sum += __shfl_xor(sum, 16); sum += __shfl_xor(sum, 32);
;         const float mean = sum * (1.f / 64.f); float var = 0.f;
; #pragma unroll
;         for (int et = 0; et < 4; ++et) { ao[et] = ao[et] - mean; var += (ao[et][0] * ao[et][0] + ao[et][1] * ao[et][1]) + (ao[et][2] * ao[et][2] + ao[et][3] * ao[et][3]); }
;         var += __shfl_xor(var, 16); var += __shfl_xor(var, 32);
.LBB0_439:
	ds_read_b128 v[54:57], v122 offset:54272
	ds_read_b128 v[126:129], v122 offset:54336
	ds_read_b128 v[130:133], v116 offset:54272
	ds_read_b128 v[134:137], v116 offset:54336
	s_waitcnt lgkmcnt(3)
	v_mfma_f32_16x16x32_bf16 v[54:57], v[54:57], v[34:37], 0
	ds_read_b128 v[138:141], v122 offset:58880
	ds_read_b128 v[142:145], v122 offset:58944
	v_mul_f32_e32 v147, v65, v61
	s_waitcnt lgkmcnt(3)
	v_mfma_f32_16x16x32_bf16 v[130:133], v[130:133], v[34:37], 0
	v_exp_f32_e32 v65, v147
	s_mov_b32 s72, 0xf800000
	v_mfma_f32_16x16x32_bf16 v[54:57], v[126:129], v[30:33], v[54:57]
	v_mov_b32_e32 v146, v65
	s_lshl_b32 s88, s11, 1
	s_add_i32 s33, s33, s7
	s_waitcnt lgkmcnt(2)
	v_mfma_f32_16x16x32_bf16 v[126:129], v[134:137], v[30:33], v[130:133]
	s_nop 2
	ds_read_b128 v[130:133], v116 offset:58880
	ds_read_b128 v[134:137], v116 offset:58944
	v_pk_fma_f32 v[48:49], v[146:147], v[56:57], v[48:49] op_sel_hi:[0,1,1]
	v_pk_fma_f32 v[54:55], v[146:147], v[54:55], v[46:47] op_sel_hi:[0,1,1]
	s_waitcnt lgkmcnt(3)
	v_mfma_f32_16x16x32_bf16 v[138:141], v[138:141], v[34:37], 0
	v_pk_mov_b32 v[46:47], v[54:55], v[48:49] op_sel:[1,0]
	v_mov_b32_e32 v56, v54
	v_mov_b32_e32 v57, v49
	s_waitcnt lgkmcnt(1)
	v_mfma_f32_16x16x32_bf16 v[34:37], v[130:133], v[34:37], 0
	v_add_f32_e64 v46, v46, v56
	v_add_f32_e64 v47, v47, v57
	v_pk_fma_f32 v[44:45], v[146:147], v[128:129], v[44:45] op_sel_hi:[0,1,1]
	v_add_f32_e32 v46, v46, v47
	v_mfma_f32_16x16x32_bf16 v[138:141], v[142:145], v[30:33], v[138:141]
	v_add_f32_e32 v56, 0, v46
	v_pk_fma_f32 v[46:47], v[146:147], v[126:127], v[42:43] op_sel_hi:[0,1,1]
	s_add_i32 s6, s6, s2
	s_waitcnt lgkmcnt(0)
	v_mfma_f32_16x16x32_bf16 v[32:35], v[134:137], v[30:33], v[34:37]
	v_pk_mov_b32 v[30:31], v[46:47], v[44:45] op_sel:[1,0]
	s_nop 1
	v_pk_fma_f32 v[40:41], v[146:147], v[140:141], v[40:41] op_sel_hi:[0,1,1]
	v_pk_fma_f32 v[38:39], v[146:147], v[138:139], v[38:39] op_sel_hi:[0,1,1]
	v_mov_b32_e32 v36, v46
	v_mov_b32_e32 v37, v45
	v_pk_add_f32 v[30:31], v[30:31], v[36:37]
	v_pk_fma_f32 v[32:33], v[146:147], v[32:33], v[50:51] op_sel_hi:[0,1,1]
	v_pk_add_f32 v[36:37], v[30:31], v[30:31] op_sel:[0,1] op_sel_hi:[1,0]
	v_pk_fma_f32 v[30:31], v[146:147], v[34:35], v[52:53] op_sel_hi:[0,1,1]
	v_add_f32_e32 v42, v38, v39
	v_add_f32_e32 v126, v40, v41
	v_mov_b32_e32 v57, v32
	v_mov_b32_e32 v37, v33
	v_mov_b32_e32 v43, v30
	v_mov_b32_e32 v127, v31
	v_pk_add_f32 v[34:35], v[56:57], v[36:37]
	v_pk_add_f32 v[36:37], v[42:43], v[126:127]
	s_add_i32 s3, s3, s0
	v_pk_add_f32 v[34:35], v[34:35], v[36:37]
	v_lshl_add_u64 v[62:63], v[62:63], 0, s[4:5]
	v_add_f32_e32 v34, v34, v35
	ds_bpermute_b32 v35, v78, v34
	s_waitcnt lgkmcnt(0)
	v_add_f32_e32 v34, v34, v35
	ds_bpermute_b32 v35, v79, v34
	s_waitcnt lgkmcnt(0)
	v_add_f32_e32 v56, v34, v35
	v_fmamk_f32 v55, v56, 0xbc800000, v55
	v_fmac_f32_e32 v54, 0xbc800000, v56
	v_fmamk_f32 v49, v56, 0xbc800000, v49
	v_fmac_f32_e32 v48, 0xbc800000, v56
	v_pk_mul_f32 v[34:35], v[48:49], v[48:49]
	v_pk_mul_f32 v[36:37], v[54:55], v[54:55]
	v_fmamk_f32 v47, v56, 0xbc800000, v47
	v_pk_mov_b32 v[42:43], v[36:37], v[34:35] op_sel:[1,0]
	v_mov_b32_e32 v37, v35
	v_pk_add_f32 v[34:35], v[42:43], v[36:37]
	v_fmac_f32_e32 v46, 0xbc800000, v56
	v_fmamk_f32 v45, v56, 0xbc800000, v45
	v_fmac_f32_e32 v44, 0xbc800000, v56
	v_pk_add_f32 v[36:37], v[34:35], v[34:35] op_sel_hi:[0,1]
	v_pk_mul_f32 v[34:35], v[44:45], v[44:45]
	v_pk_mul_f32 v[42:43], v[46:47], v[46:47]
	v_fmac_f32_e32 v38, 0xbc800000, v56
	v_pk_mov_b32 v[50:51], v[42:43], v[34:35] op_sel:[1,0]
	v_mov_b32_e32 v43, v35
	v_pk_add_f32 v[34:35], v[50:51], v[42:43]
	v_fmamk_f32 v39, v56, 0xbc800000, v39
	v_pk_add_f32 v[42:43], v[34:35], v[34:35] op_sel_hi:[0,1]
	v_fmac_f32_e32 v40, 0xbc800000, v56
	v_mul_f32_e32 v34, v38, v38
	v_fmamk_f32 v41, v56, 0xbc800000, v41
	v_pk_fma_f32 v[50:51], v[38:39], v[38:39], v[34:35] op_sel_hi:[1,1,0]
	v_mul_f32_e32 v34, v40, v40
	v_pk_fma_f32 v[52:53], v[40:41], v[40:41], v[34:35] op_sel_hi:[1,1,0]
	v_fmamk_f32 v35, v56, 0xbc800000, v31
	v_fmac_f32_e32 v30, 0xbc800000, v56
	v_fmamk_f32 v34, v56, 0xbc800000, v33
	v_fmac_f32_e32 v32, 0xbc800000, v56
	v_mul_f32_e32 v50, v32, v32
	v_mul_f32_e32 v52, v34, v34
	v_mul_f32_e32 v36, v30, v30
	v_mul_f32_e32 v42, v35, v35
	v_pk_add_f32 v[50:51], v[50:51], v[52:53]
	v_pk_add_f32 v[36:37], v[36:37], v[42:43]
	s_waitcnt vmcnt(3)
	v_and_b32_e32 v52, 0xffff0000, v72
	v_pk_add_f32 v[36:37], v[50:51], v[36:37]
	v_lshlrev_b32_e32 v50, 16, v72
	v_add_f32_e32 v31, v36, v37
	ds_bpermute_b32 v33, v78, v31
	v_lshlrev_b32_e32 v51, 16, v73
	v_and_b32_e32 v53, 0xffff0000, v73
	s_waitcnt lgkmcnt(0)
	v_add_f32_e32 v31, v31, v33
	ds_bpermute_b32 v33, v79, v31
	s_waitcnt lgkmcnt(0)
; __device__ __forceinline__ unsigned pk2(float lo, float hi) { return f2bf(lo) | (f2bf(hi) << 16); }
; __device__ __forceinline__ float bflo(unsigned w) { return __uint_as_float(w << 16); }
; __device__ __forceinline__ float bfhi(unsigned w) { return __uint_as_float(w & 0xffff0000u); }
; __device__ __forceinline__ float sigm(float x) { return __builtin_amdgcn_rcpf(1.f + __expf(-x)); }
; __device__ __forceinline__ void ret_out_phase(const Frame& F, const bf16* P0, const bf16* RT, bf16* MIX) {
;     ...
;         var += __shfl_xor(var, 16); var += __shfl_xor(var, 32);
;         const float rstd = 1.f / sqrtf(var * (1.f / 64.f) + EPS);
;         bf16* op = MIX + (size_t)(rowbase + t) * DM_ + 64 * h + 4 * fq;
; #pragma unroll
;         for (int et = 0; et < 4; ++et) { const v2u gw = gwv[et]; const float g0 = bflo(gw.x), g1 = bfhi(gw.x), g2 = bflo(gw.y), g3 = bfhi(gw.y);
;             v2u ow; ow.x = pk2(g0 * sigm(g0) * ao[et][0] * rstd, g1 * sigm(g1) * ao[et][1] * rstd); ow.y = pk2(g2 * sigm(g2) * ao[et][2] * rstd, g3 * sigm(g3) * ao[et][3] * rstd);
;             *(v2u*)(op + 16 * et) = ow; }
	v_add_f32_e32 v31, v31, v33
	v_fmamk_f32 v31, v31, 0x3c800000, v117
	v_mul_f32_e32 v33, 0x4f800000, v31
	v_cmp_gt_f32_e32 vcc, s72, v31
	s_nop 1
	v_cndmask_b32_e32 v31, v31, v33, vcc
	v_sqrt_f32_e32 v33, v31
	s_nop 0
	v_add_u32_e32 v36, -1, v33
	v_fma_f32 v37, -v36, v33, v31
	v_cmp_ge_f32_e64 s[72:73], 0, v37
	v_add_u32_e32 v37, 1, v33
	s_nop 0
	v_cndmask_b32_e64 v36, v33, v36, s[72:73]
	v_fma_f32 v33, -v37, v33, v31
	v_cmp_lt_f32_e64 s[72:73], 0, v33
	s_nop 1
	v_cndmask_b32_e64 v33, v36, v37, s[72:73]
	v_mul_f32_e32 v36, 0x37800000, v33
	v_cndmask_b32_e32 v33, v33, v36, vcc
	v_cmp_class_f32_e32 vcc, v31, v118
	s_nop 1
	v_cndmask_b32_e32 v31, v33, v31, vcc
	v_div_scale_f32 v33, s[72:73], v31, v31, 1.0
	v_rcp_f32_e32 v36, v33
	s_nop 0
	v_fma_f32 v37, -v33, v36, 1.0
	v_fmac_f32_e32 v36, v37, v36
	v_div_scale_f32 v37, vcc, 1.0, v31, 1.0
	v_mul_f32_e32 v42, v37, v36
	v_fma_f32 v43, -v33, v42, v37
	v_fmac_f32_e32 v42, v43, v36
	v_fma_f32 v33, -v33, v42, v37
	v_div_fmas_f32 v33, v33, v36, v42
	v_div_fixup_f32 v42, v33, v31, 1.0
	v_mul_f32_e32 v31, 0xbfb8aa3b, v50
	v_exp_f32_e32 v31, v31
	v_mul_f32_e32 v33, 0xbfb8aa3b, v52
	v_mul_f32_e32 v43, 0xbfb8aa3b, v51
	v_exp_f32_e32 v33, v33
	v_exp_f32_e32 v43, v43
	v_add_f32_e32 v31, 1.0, v31
	v_rcp_f32_e32 v56, v31
	v_add_f32_e32 v31, 1.0, v33
	v_add_f32_e32 v33, 1.0, v43
	v_rcp_f32_e32 v57, v33
	v_mul_f32_e32 v33, 0xbfb8aa3b, v53
	v_exp_f32_e32 v33, v33
	v_rcp_f32_e32 v72, v31
	v_pk_mul_f32 v[50:51], v[56:57], v[50:51]
	v_mov_b32_e32 v56, v54
	v_add_f32_e32 v31, 1.0, v33
	v_rcp_f32_e32 v73, v31
	v_mov_b32_e32 v57, v48
	v_pk_mul_f32 v[50:51], v[50:51], v[56:57]
	v_mov_b32_e32 v48, v55
	v_pk_mul_f32 v[52:53], v[72:73], v[52:53]
	v_pk_mul_f32 v[50:51], v[50:51], v[42:43] op_sel_hi:[1,0]
	v_pk_mul_f32 v[48:49], v[52:53], v[48:49]
	v_and_b32_sdwa v33, v50, v125 dst_sel:DWORD dst_unused:UNUSED_PAD src0_sel:WORD_1 src1_sel:DWORD
	v_pk_mul_f32 v[48:49], v[48:49], v[42:43] op_sel_hi:[1,0]
	v_lshlrev_b64 v[36:37], 11, v[74:75]
	v_add3_u32 v33, v50, v33, s8
	v_and_b32_sdwa v43, v49, v125 dst_sel:DWORD dst_unused:UNUSED_PAD src0_sel:WORD_1 src1_sel:DWORD
	v_and_b32_sdwa v50, v48, v125 dst_sel:DWORD dst_unused:UNUSED_PAD src0_sel:WORD_1 src1_sel:DWORD
	v_lshl_add_u64 v[36:37], s[86:87], 0, v[36:37]
	v_and_b32_sdwa v31, v51, v125 dst_sel:DWORD dst_unused:UNUSED_PAD src0_sel:WORD_1 src1_sel:DWORD
	v_add3_u32 v43, v49, v43, s8
	v_add3_u32 v48, v48, v50, s8
	v_lshl_add_u64 v[36:37], v[36:37], 0, s[88:89]
	v_add3_u32 v31, v51, v31, s8
	v_and_b32_e32 v43, 0xffff0000, v43
	v_and_b32_e32 v48, 0xffff0000, v48
	v_lshl_add_u64 v[36:37], v[36:37], 0, v[58:59]
	v_or_b32_sdwa v49, v43, v31 dst_sel:DWORD dst_unused:UNUSED_PAD src0_sel:DWORD src1_sel:WORD_1
	v_or_b32_sdwa v48, v48, v33 dst_sel:DWORD dst_unused:UNUSED_PAD src0_sel:DWORD src1_sel:WORD_1
	global_store_dwordx2 v[36:37], v[48:49], off
	s_waitcnt vmcnt(3)
	v_lshlrev_b32_e32 v48, 16, v70
	v_lshlrev_b32_e32 v49, 16, v71
	v_and_b32_e32 v50, 0xffff0000, v70
	v_mul_f32_e32 v31, 0xbfb8aa3b, v48
	v_exp_f32_e32 v31, v31
	v_mul_f32_e32 v33, 0xbfb8aa3b, v50
	v_mul_f32_e32 v43, 0xbfb8aa3b, v49
	v_exp_f32_e32 v33, v33
	v_exp_f32_e32 v43, v43
	v_add_f32_e32 v31, 1.0, v31
	v_and_b32_e32 v51, 0xffff0000, v71
	v_rcp_f32_e32 v52, v31
	v_add_f32_e32 v31, 1.0, v33
	v_add_f32_e32 v33, 1.0, v43
	v_rcp_f32_e32 v53, v33
	v_mul_f32_e32 v33, 0xbfb8aa3b, v51
	v_exp_f32_e32 v33, v33
	v_rcp_f32_e32 v54, v31
	v_pk_mul_f32 v[48:49], v[52:53], v[48:49]
	v_mov_b32_e32 v53, v44
	v_add_f32_e32 v31, 1.0, v33
	v_rcp_f32_e32 v55, v31
	v_mov_b32_e32 v44, v47
	v_mov_b32_e32 v52, v46
	v_pk_mul_f32 v[48:49], v[48:49], v[52:53]
	v_pk_mul_f32 v[50:51], v[54:55], v[50:51]
	v_pk_mul_f32 v[48:49], v[48:49], v[42:43] op_sel_hi:[1,0]
	v_pk_mul_f32 v[44:45], v[50:51], v[44:45]
	v_and_b32_sdwa v31, v49, v125 dst_sel:DWORD dst_unused:UNUSED_PAD src0_sel:WORD_1 src1_sel:DWORD
	v_pk_mul_f32 v[44:45], v[44:45], v[42:43] op_sel_hi:[1,0]
	v_and_b32_sdwa v33, v48, v125 dst_sel:DWORD dst_unused:UNUSED_PAD src0_sel:WORD_1 src1_sel:DWORD
	v_and_b32_sdwa v43, v45, v125 dst_sel:DWORD dst_unused:UNUSED_PAD src0_sel:WORD_1 src1_sel:DWORD
	v_and_b32_sdwa v46, v44, v125 dst_sel:DWORD dst_unused:UNUSED_PAD src0_sel:WORD_1 src1_sel:DWORD
	v_add3_u32 v43, v45, v43, s8
	v_add3_u32 v44, v44, v46, s8
	v_add3_u32 v33, v48, v33, s8
	v_add3_u32 v31, v49, v31, s8
	v_and_b32_e32 v43, 0xffff0000, v43
	v_and_b32_e32 v44, 0xffff0000, v44
	v_or_b32_sdwa v45, v43, v31 dst_sel:DWORD dst_unused:UNUSED_PAD src0_sel:DWORD src1_sel:WORD_1
	v_or_b32_sdwa v44, v44, v33 dst_sel:DWORD dst_unused:UNUSED_PAD src0_sel:DWORD src1_sel:WORD_1
	global_store_dwordx2 v[36:37], v[44:45], off offset:32
	s_waitcnt vmcnt(3)
; __device__ __forceinline__ unsigned pk2(float lo, float hi) { return f2bf(lo) | (f2bf(hi) << 16); }
; __device__ __forceinline__ float bflo(unsigned w) { return __uint_as_float(w << 16); }
; __device__ __forceinline__ float bfhi(unsigned w) { return __uint_as_float(w & 0xffff0000u); }
; __device__ __forceinline__ float sigm(float x) { return __builtin_amdgcn_rcpf(1.f + __expf(-x)); }
; __device__ __forceinline__ void ret_out_phase(const Frame& F, const bf16* P0, const bf16* RT, bf16* MIX) {
;     ...
; #pragma unroll
;         for (int et = 0; et < 4; ++et) { const v2u gw = gwv[et]; const float g0 = bflo(gw.x), g1 = bfhi(gw.x), g2 = bflo(gw.y), g3 = bfhi(gw.y);
;             v2u ow; ow.x = pk2(g0 * sigm(g0) * ao[et][0] * rstd, g1 * sigm(g1) * ao[et][1] * rstd); ow.y = pk2(g2 * sigm(g2) * ao[et][2] * rstd, g3 * sigm(g3) * ao[et][3] * rstd);
;             *(v2u*)(op + 16 * et) = ow; }
;     }
	v_lshlrev_b32_e32 v44, 16, v68
	v_lshlrev_b32_e32 v45, 16, v69
	v_and_b32_e32 v46, 0xffff0000, v68
	v_mul_f32_e32 v31, 0xbfb8aa3b, v44
	v_exp_f32_e32 v31, v31
	v_mul_f32_e32 v33, 0xbfb8aa3b, v46
	v_mul_f32_e32 v43, 0xbfb8aa3b, v45
	v_exp_f32_e32 v33, v33
	v_exp_f32_e32 v43, v43
	v_add_f32_e32 v31, 1.0, v31
	v_and_b32_e32 v47, 0xffff0000, v69
	v_rcp_f32_e32 v48, v31
	v_add_f32_e32 v31, 1.0, v33
	v_add_f32_e32 v33, 1.0, v43
	v_rcp_f32_e32 v49, v33
	v_mul_f32_e32 v33, 0xbfb8aa3b, v47
	v_exp_f32_e32 v33, v33
	v_rcp_f32_e32 v50, v31
	v_pk_mul_f32 v[44:45], v[48:49], v[44:45]
	v_mov_b32_e32 v49, v40
	v_add_f32_e32 v31, 1.0, v33
	v_rcp_f32_e32 v51, v31
	v_mov_b32_e32 v40, v39
	v_mov_b32_e32 v48, v38
	v_pk_mul_f32 v[44:45], v[44:45], v[48:49]
	v_pk_mul_f32 v[46:47], v[50:51], v[46:47]
	v_pk_mul_f32 v[44:45], v[44:45], v[42:43] op_sel_hi:[1,0]
	v_pk_mul_f32 v[38:39], v[46:47], v[40:41]
	v_and_b32_sdwa v31, v45, v125 dst_sel:DWORD dst_unused:UNUSED_PAD src0_sel:WORD_1 src1_sel:DWORD
	v_pk_mul_f32 v[38:39], v[38:39], v[42:43] op_sel_hi:[1,0]
	v_and_b32_sdwa v33, v44, v125 dst_sel:DWORD dst_unused:UNUSED_PAD src0_sel:WORD_1 src1_sel:DWORD
	v_and_b32_sdwa v40, v39, v125 dst_sel:DWORD dst_unused:UNUSED_PAD src0_sel:WORD_1 src1_sel:DWORD
	v_and_b32_sdwa v41, v38, v125 dst_sel:DWORD dst_unused:UNUSED_PAD src0_sel:WORD_1 src1_sel:DWORD
	v_add3_u32 v39, v39, v40, s8
	v_add3_u32 v38, v38, v41, s8
	v_add3_u32 v33, v44, v33, s8
	v_add3_u32 v31, v45, v31, s8
	v_and_b32_e32 v39, 0xffff0000, v39
	v_and_b32_e32 v38, 0xffff0000, v38
	v_or_b32_sdwa v39, v39, v31 dst_sel:DWORD dst_unused:UNUSED_PAD src0_sel:DWORD src1_sel:WORD_1
	v_or_b32_sdwa v38, v38, v33 dst_sel:DWORD dst_unused:UNUSED_PAD src0_sel:DWORD src1_sel:WORD_1
	global_store_dwordx2 v[36:37], v[38:39], off offset:64
	s_waitcnt vmcnt(3)
	v_lshlrev_b32_e32 v38, 16, v66
	v_mul_f32_e32 v31, 0xbfb8aa3b, v38
	v_lshlrev_b32_e32 v39, 16, v67
	v_exp_f32_e32 v31, v31
	v_mul_f32_e32 v33, 0xbfb8aa3b, v39
	v_exp_f32_e32 v33, v33
	v_and_b32_e32 v40, 0xffff0000, v66
	v_add_f32_e32 v31, 1.0, v31
	v_and_b32_e32 v41, 0xffff0000, v67
	v_rcp_f32_e32 v44, v31
	v_mul_f32_e32 v31, 0xbfb8aa3b, v40
	v_add_f32_e32 v33, 1.0, v33
	v_exp_f32_e32 v31, v31
	v_rcp_f32_e32 v45, v33
	v_mul_f32_e32 v33, 0xbfb8aa3b, v41
	v_exp_f32_e32 v33, v33
	v_add_f32_e32 v31, 1.0, v31
	v_rcp_f32_e32 v46, v31
	v_pk_mul_f32 v[38:39], v[44:45], v[38:39]
	v_add_f32_e32 v31, 1.0, v33
	v_rcp_f32_e32 v47, v31
	v_mov_b32_e32 v33, v30
	v_pk_mul_f32 v[30:31], v[38:39], v[32:33]
	s_andn2_b64 vcc, exec, s[74:75]
	v_pk_mul_f32 v[32:33], v[46:47], v[40:41]
	v_pk_mul_f32 v[30:31], v[30:31], v[42:43] op_sel_hi:[1,0]
	v_pk_mul_f32 v[32:33], v[32:33], v[34:35]
	v_and_b32_sdwa v34, v31, v125 dst_sel:DWORD dst_unused:UNUSED_PAD src0_sel:WORD_1 src1_sel:DWORD
	v_pk_mul_f32 v[32:33], v[32:33], v[42:43] op_sel_hi:[1,0]
	v_and_b32_sdwa v35, v30, v125 dst_sel:DWORD dst_unused:UNUSED_PAD src0_sel:WORD_1 src1_sel:DWORD
	v_add3_u32 v30, v30, v35, s8
	v_add3_u32 v31, v31, v34, s8
	v_and_b32_sdwa v34, v33, v125 dst_sel:DWORD dst_unused:UNUSED_PAD src0_sel:WORD_1 src1_sel:DWORD
	v_and_b32_sdwa v35, v32, v125 dst_sel:DWORD dst_unused:UNUSED_PAD src0_sel:WORD_1 src1_sel:DWORD
	v_add3_u32 v33, v33, v34, s8
	v_add3_u32 v32, v32, v35, s8
	v_and_b32_e32 v33, 0xffff0000, v33
	v_and_b32_e32 v32, 0xffff0000, v32
	v_or_b32_sdwa v31, v33, v31 dst_sel:DWORD dst_unused:UNUSED_PAD src0_sel:DWORD src1_sel:WORD_1
	v_or_b32_sdwa v30, v32, v30 dst_sel:DWORD dst_unused:UNUSED_PAD src0_sel:DWORD src1_sel:WORD_1
	global_store_dwordx2 v[36:37], v[30:31], off offset:96
	s_cbranch_vccz .LBB0_450

; #define LAS __attribute__((address_space(3)))
; __device__ __forceinline__ unsigned pk2(float lo, float hi) { return f2bf(lo) | (f2bf(hi) << 16); }
; __device__ __forceinline__ void ret_out_phase(const Frame& F, const bf16* P0, const bf16* RT, bf16* MIX) {
;     ...
;         for (int c32 = 0; c32 < 4; ++c32) { if (c32 <= (w >> 1)) {
;             const LAS bf16* kp = Ks + (32 * c32 + fr) * QK_LD + 8 * fq;
;             const bf16x8 kA0 = *(const LAS bf16x8*)kp, kA1 = *(const LAS bf16x8*)(kp + 32), kB0 = *(const LAS bf16x8*)(kp + 16 * QK_LD), kB1 = *(const LAS bf16x8*)(kp + 16 * QK_LD + 32);
;             pg8::f32x4 s0 = {0.f, 0.f, 0.f, 0.f}, s1 = {0.f, 0.f, 0.f, 0.f};
;             s0 = __builtin_amdgcn_mfma_f32_16x16x32_bf16(kA0, q0, s0, 0, 0, 0); s0 = __builtin_amdgcn_mfma_f32_16x16x32_bf16(kA1, q1, s0, 0, 0, 0);
;             s1 = __builtin_amdgcn_mfma_f32_16x16x32_bf16(kB0, q0, s1, 0, 0, 0); s1 = __builtin_amdgcn_mfma_f32_16x16x32_bf16(kB1, q1, s1, 0, 0, 0);
;             float pvv[8];
; #pragma unroll
;             for (int j = 0; j < 4; ++j) { const int sA = 32 * c32 + 4 * fq + j, rA = t - sA, rB = rA - 16;
;                 pvv[j] = rA >= 0 ? s0[j] * exp2f((float)rA * lg) : 0.f; pvv[4 + j] = rB >= 0 ? s1[j] * exp2f((float)rB * lg) : 0.f; }
;             v4u pw; pw.x = pk2(pvv[0], pvv[1]); pw.y = pk2(pvv[2], pvv[3]); pw.z = pk2(pvv[4], pvv[5]); pw.w = pk2(pvv[6], pvv[7]);
;             const bf16x8 pb = __builtin_bit_cast(bf16x8, pw);
; #pragma unroll
;             for (int et = 0; et < 4; ++et) { const LAS bf16* vp = Vt + (16 * et + fr) * VT_LD + 32 * c32 + 4 * fq; const v2u lo = *(const LAS v2u*)vp, hi = *(const LAS v2u*)(vp + 16);
;                 v4u aw; aw.x = lo.x; aw.y = lo.y; aw.z = hi.x; aw.w = hi.y;
;                 ao[et] = __builtin_amdgcn_mfma_f32_16x16x32_bf16(__builtin_bit_cast(bf16x8, aw), pb, ao[et], 0, 0, 0); }
;         } }
.LBB0_446:
	ds_read_b128 v[38:41], v122 offset:35840
	ds_read_b128 v[42:45], v122 offset:35904
	ds_read_b128 v[46:49], v122 offset:38144
	ds_read_b128 v[50:53], v122 offset:38208
	s_waitcnt lgkmcnt(3)
	v_mfma_f32_16x16x32_bf16 v[38:41], v[38:41], v[34:37], 0
	v_readlane_b32 s72, v254, 5
	s_waitcnt lgkmcnt(1)
	v_mfma_f32_16x16x32_bf16 v[46:49], v[46:49], v[34:37], 0
	v_readlane_b32 s73, v254, 6
	v_mfma_f32_16x16x32_bf16 v[38:41], v[42:45], v[30:33], v[38:41]
	v_mul_f32_e32 v42, v65, v82
	v_exp_f32_e32 v56, v42
	s_waitcnt lgkmcnt(0)
	v_mfma_f32_16x16x32_bf16 v[42:45], v[50:53], v[30:33], v[46:49]
	s_nop 2
	v_mul_f32_e32 v46, v65, v83
	v_exp_f32_e32 v48, v46
	v_mul_f32_e32 v46, v65, v84
	v_exp_f32_e32 v50, v46
	s_nop 0
	v_mul_f32_e32 v46, v65, v85
	v_exp_f32_e32 v52, v46
	v_mov_b32_e32 v46, v56
	v_mul_f32_e32 v49, v65, v86
	v_mul_f32_e32 v53, v65, v87
	v_exp_f32_e32 v49, v49
	v_mul_f32_e32 v55, v65, v88
	v_exp_f32_e32 v53, v53
	v_exp_f32_e32 v55, v55
	v_mov_b32_e32 v47, v49
	v_mov_b32_e32 v49, v53
	v_mov_b32_e32 v51, v55
	v_mov_b32_e32 v55, v40
	v_mov_b32_e32 v40, v39
	v_mul_f32_e32 v57, v65, v89
	v_mov_b32_e32 v54, v38
	v_pk_mul_f32 v[38:39], v[50:51], v[40:41]
	v_exp_f32_e32 v57, v57
	v_cndmask_b32_e64 v50, v38, 0, s[20:21]
	v_cndmask_b32_e64 v51, v39, 0, s[18:19]
	v_mov_b32_e32 v38, v42
	v_mov_b32_e32 v39, v44
	v_pk_mul_f32 v[38:39], v[48:49], v[38:39]
	v_cndmask_b32_e64 v39, 0, v39, s[72:73]
	v_readlane_b32 s72, v254, 9
	v_readlane_b32 s73, v254, 10
	v_mov_b32_e32 v53, v57
	v_mov_b32_e32 v44, v43
	v_cndmask_b32_e64 v38, 0, v38, s[72:73]
	v_readlane_b32 s72, v254, 7
	v_pk_mul_f32 v[40:41], v[52:53], v[44:45]
	v_readlane_b32 s73, v254, 8
	v_pk_mul_f32 v[46:47], v[46:47], v[54:55]
	v_cndmask_b32_e64 v40, 0, v40, s[12:13]
	v_cndmask_b32_e64 v41, 0, v41, s[72:73]
	v_cndmask_b32_e64 v47, v47, 0, s[16:17]
	v_cndmask_b32_e64 v46, v46, 0, s[14:15]
	v_bfe_u32 v42, v41, 16, 1
	v_bfe_u32 v43, v40, 16, 1
	v_add3_u32 v43, v40, v43, s8
	v_add3_u32 v42, v41, v42, s8
	v_bfe_u32 v40, v46, 16, 1
	v_bfe_u32 v41, v47, 16, 1
	v_bfe_u32 v48, v38, 16, 1
	v_bfe_u32 v49, v39, 16, 1
	v_add3_u32 v49, v39, v49, s8
	v_add3_u32 v48, v38, v48, s8
	v_add3_u32 v47, v47, v41, s8
	v_add3_u32 v46, v46, v40, s8
	ds_read2_b64 v[38:41], v123 offset1:4
	v_bfe_u32 v44, v51, 16, 1
	v_bfe_u32 v45, v50, 16, 1
	v_add3_u32 v45, v50, v45, s8
	v_add3_u32 v44, v51, v44, s8
	v_lshrrev_b32_e32 v46, 16, v46
	v_lshrrev_b32_e32 v47, 16, v47
	v_lshrrev_b32_e32 v48, 16, v48
	v_lshrrev_b32_e32 v49, 16, v49
	v_and_or_b32 v53, v42, s9, v49
	v_and_or_b32 v52, v43, s9, v48
	v_and_or_b32 v51, v44, s9, v47
	v_and_or_b32 v50, v45, s9, v46
	ds_read2_b64 v[54:57], v127 offset0:96 offset1:100
	s_waitcnt lgkmcnt(1)
	v_mfma_f32_16x16x32_bf16 v[46:49], v[38:41], v[50:53], 0
	ds_read2_b64 v[38:41], v128 offset0:32 offset1:36
	s_waitcnt lgkmcnt(0)
	v_mfma_f32_16x16x32_bf16 v[42:45], v[38:41], v[50:53], 0
	ds_read2_b64 v[38:41], v126 offset0:64 offset1:68
	v_mfma_f32_16x16x32_bf16 v[54:57], v[54:57], v[50:53], 0
	s_waitcnt lgkmcnt(0)
	v_mfma_f32_16x16x32_bf16 v[38:41], v[38:41], v[50:53], 0
	s_nop 5
	v_mov_b32_e32 v50, v54
	v_mov_b32_e32 v51, v55
	v_mov_b32_e32 v52, v56
	v_mov_b32_e32 v53, v57
	s_andn2_b64 vcc, exec, s[92:93]
	s_cbranch_vccnz .LBB0_444
.LBB0_447:
	ds_read_b128 v[50:53], v122 offset:40448
	ds_read_b128 v[130:133], v122 offset:40512
	ds_read_b128 v[134:137], v122 offset:42752
	ds_read_b128 v[138:141], v122 offset:42816
	s_waitcnt lgkmcnt(3)
	v_mfma_f32_16x16x32_bf16 v[50:53], v[50:53], v[34:37], 0
	s_waitcnt lgkmcnt(1)
	v_mfma_f32_16x16x32_bf16 v[134:137], v[134:137], v[34:37], 0
	v_mfma_f32_16x16x32_bf16 v[50:53], v[130:133], v[30:33], v[50:53]
	v_mul_f32_e32 v130, v65, v90
	v_exp_f32_e32 v143, v130
	s_waitcnt lgkmcnt(0)
	v_mfma_f32_16x16x32_bf16 v[130:133], v[138:141], v[30:33], v[134:137]
	v_mul_f32_e32 v141, v65, v96
	s_nop 1
	v_mul_f32_e32 v134, v65, v91
	v_exp_f32_e32 v136, v134
	s_nop 0
	v_mul_f32_e32 v134, v65, v92
	v_exp_f32_e32 v138, v134
	v_mul_f32_e32 v134, v65, v93
	v_exp_f32_e32 v140, v134
	v_mov_b32_e32 v134, v143
	v_mul_f32_e32 v135, v65, v94
	v_exp_f32_e32 v135, v135
	v_cmp_gt_f32_e32 vcc, s1, v141
	v_mul_f32_e32 v139, v65, v95
	v_exp_f32_e32 v139, v139
	v_cndmask_b32_e32 v141, 0, v124, vcc
	v_cndmask_b32_e32 v142, 0, v119, vcc
	v_fmac_f32_e32 v142, v65, v96
	v_exp_f32_e32 v142, v142
	v_mul_f32_e32 v144, v65, v97
	v_exp_f32_e32 v144, v144
	v_mov_b32_e32 v137, v139
	v_ldexp_f32 v139, v142, v141
	v_mov_b32_e32 v141, v144
	v_mov_b32_e32 v143, v52
	v_mov_b32_e32 v52, v51
	v_mov_b32_e32 v142, v50
	v_pk_mul_f32 v[50:51], v[138:139], v[52:53]
	v_pk_mul_f32 v[134:135], v[134:135], v[142:143]
	v_cndmask_b32_e64 v138, v51, 0, s[36:37]
	v_mov_b32_e32 v51, v132
	v_mov_b32_e32 v132, v131
	v_cndmask_b32_e64 v129, v135, 0, s[30:31]
	v_cndmask_b32_e64 v135, v50, 0, s[38:39]
	v_mov_b32_e32 v50, v130
	v_pk_mul_f32 v[52:53], v[140:141], v[132:133]
	v_pk_mul_f32 v[50:51], v[136:137], v[50:51]
	v_cndmask_b32_e64 v52, 0, v52, s[28:29]
	v_cndmask_b32_e64 v53, 0, v53, s[26:27]
	v_cndmask_b32_e64 v134, v134, 0, s[34:35]
	v_cndmask_b32_e64 v51, 0, v51, s[22:23]
	v_cndmask_b32_e64 v50, 0, v50, s[24:25]
	v_bfe_u32 v130, v53, 16, 1
	v_bfe_u32 v131, v52, 16, 1
	v_bfe_u32 v132, v138, 16, 1
	v_bfe_u32 v133, v135, 16, 1
	v_add3_u32 v135, v135, v133, s8
	v_add3_u32 v136, v138, v132, s8
	v_add3_u32 v131, v52, v131, s8
	v_add3_u32 v130, v53, v130, s8
	v_bfe_u32 v52, v134, 16, 1
	v_bfe_u32 v53, v129, 16, 1
	v_bfe_u32 v132, v50, 16, 1
	v_bfe_u32 v133, v51, 16, 1
	v_add3_u32 v133, v51, v133, s8
	v_add3_u32 v132, v50, v132, s8
	v_add3_u32 v129, v129, v53, s8
	v_add3_u32 v134, v134, v52, s8
	ds_read2_b64 v[50:53], v123 offset0:8 offset1:12
	v_lshrrev_b32_e32 v134, 16, v134
	v_lshrrev_b32_e32 v129, 16, v129
	v_lshrrev_b32_e32 v132, 16, v132
	v_lshrrev_b32_e32 v133, 16, v133
	v_and_or_b32 v133, v130, s9, v133
	v_and_or_b32 v132, v131, s9, v132
	v_and_or_b32 v131, v136, s9, v129
	v_and_or_b32 v130, v135, s9, v134
	s_waitcnt lgkmcnt(0)
	s_nop 0
	v_mfma_f32_16x16x32_bf16 v[46:49], v[50:53], v[130:133], v[46:49]
	ds_read2_b64 v[50:53], v128 offset0:40 offset1:44
	s_waitcnt lgkmcnt(0)
	v_mfma_f32_16x16x32_bf16 v[42:45], v[50:53], v[130:133], v[42:45]
	ds_read2_b64 v[50:53], v126 offset0:72 offset1:76
	s_waitcnt lgkmcnt(0)
	v_mfma_f32_16x16x32_bf16 v[38:41], v[50:53], v[130:133], v[38:41]
	ds_read2_b64 v[50:53], v127 offset0:104 offset1:108
	s_waitcnt lgkmcnt(0)
	v_mfma_f32_16x16x32_bf16 v[50:53], v[50:53], v[130:133], v[54:57]
	s_andn2_b64 vcc, exec, s[94:95]
	s_cbranch_vccnz .LBB0_445
; #define LAS __attribute__((address_space(3)))
; __device__ __forceinline__ unsigned pk2(float lo, float hi) { return f2bf(lo) | (f2bf(hi) << 16); }
; __device__ __forceinline__ void ret_out_phase(const Frame& F, const bf16* P0, const bf16* RT, bf16* MIX) {
;     ...
;         for (int c32 = 0; c32 < 4; ++c32) { if (c32 <= (w >> 1)) {
;             const LAS bf16* kp = Ks + (32 * c32 + fr) * QK_LD + 8 * fq;
;             const bf16x8 kA0 = *(const LAS bf16x8*)kp, kA1 = *(const LAS bf16x8*)(kp + 32), kB0 = *(const LAS bf16x8*)(kp + 16 * QK_LD), kB1 = *(const LAS bf16x8*)(kp + 16 * QK_LD + 32);
;             pg8::f32x4 s0 = {0.f, 0.f, 0.f, 0.f}, s1 = {0.f, 0.f, 0.f, 0.f};
;             s0 = __builtin_amdgcn_mfma_f32_16x16x32_bf16(kA0, q0, s0, 0, 0, 0); s0 = __builtin_amdgcn_mfma_f32_16x16x32_bf16(kA1, q1, s0, 0, 0, 0);
;             s1 = __builtin_amdgcn_mfma_f32_16x16x32_bf16(kB0, q0, s1, 0, 0, 0); s1 = __builtin_amdgcn_mfma_f32_16x16x32_bf16(kB1, q1, s1, 0, 0, 0);
;             float pvv[8];
; #pragma unroll
;             for (int j = 0; j < 4; ++j) { const int sA = 32 * c32 + 4 * fq + j, rA = t - sA, rB = rA - 16;
;                 pvv[j] = rA >= 0 ? s0[j] * exp2f((float)rA * lg) : 0.f; pvv[4 + j] = rB >= 0 ? s1[j] * exp2f((float)rB * lg) : 0.f; }
;             v4u pw; pw.x = pk2(pvv[0], pvv[1]); pw.y = pk2(pvv[2], pvv[3]); pw.z = pk2(pvv[4], pvv[5]); pw.w = pk2(pvv[6], pvv[7]);
;             const bf16x8 pb = __builtin_bit_cast(bf16x8, pw);
; #pragma unroll
;             for (int et = 0; et < 4; ++et) { const LAS bf16* vp = Vt + (16 * et + fr) * VT_LD + 32 * c32 + 4 * fq; const v2u lo = *(const LAS v2u*)vp, hi = *(const LAS v2u*)(vp + 16);
;                 v4u aw; aw.x = lo.x; aw.y = lo.y; aw.z = hi.x; aw.w = hi.y;
;                 ao[et] = __builtin_amdgcn_mfma_f32_16x16x32_bf16(__builtin_bit_cast(bf16x8, aw), pb, ao[et], 0, 0, 0); }
;         } }
.LBB0_448:
	s_nop 0
	ds_read_b128 v[54:57], v122 offset:45056
	ds_read_b128 v[130:133], v122 offset:45120
	ds_read_b128 v[134:137], v122 offset:47360
	ds_read_b128 v[138:141], v122 offset:47424
	s_waitcnt lgkmcnt(3)
	v_mfma_f32_16x16x32_bf16 v[54:57], v[54:57], v[34:37], 0
	s_waitcnt lgkmcnt(1)
	v_mfma_f32_16x16x32_bf16 v[134:137], v[134:137], v[34:37], 0
	v_mfma_f32_16x16x32_bf16 v[54:57], v[130:133], v[30:33], v[54:57]
	v_mul_f32_e32 v130, v65, v98
	v_exp_f32_e32 v143, v130
	s_waitcnt lgkmcnt(0)
	v_mfma_f32_16x16x32_bf16 v[130:133], v[138:141], v[30:33], v[134:137]
	v_mul_f32_e32 v141, v65, v104
	s_nop 1
	v_mul_f32_e32 v134, v65, v99
	v_exp_f32_e32 v136, v134
	s_nop 0
	v_mul_f32_e32 v134, v65, v100
	v_exp_f32_e32 v138, v134
	v_mul_f32_e32 v134, v65, v101
	v_exp_f32_e32 v140, v134
	v_mov_b32_e32 v134, v143
	v_mul_f32_e32 v135, v65, v102
	v_exp_f32_e32 v135, v135
	v_cmp_gt_f32_e32 vcc, s1, v141
	v_mul_f32_e32 v139, v65, v103
	v_exp_f32_e32 v139, v139
	v_cndmask_b32_e32 v141, 0, v124, vcc
	v_cndmask_b32_e32 v142, 0, v119, vcc
	v_fmac_f32_e32 v142, v65, v104
	v_exp_f32_e32 v142, v142
	v_mul_f32_e32 v144, v65, v105
	v_exp_f32_e32 v144, v144
	v_mov_b32_e32 v137, v139
	v_ldexp_f32 v139, v142, v141
	v_mov_b32_e32 v141, v144
	v_mov_b32_e32 v143, v56
	v_mov_b32_e32 v56, v55
	v_mov_b32_e32 v142, v54
	v_pk_mul_f32 v[54:55], v[138:139], v[56:57]
	v_pk_mul_f32 v[134:135], v[134:135], v[142:143]
	v_cndmask_b32_e64 v138, v55, 0, s[52:53]
	v_mov_b32_e32 v55, v132
	v_mov_b32_e32 v132, v131
	v_cndmask_b32_e64 v129, v135, 0, s[48:49]
	v_cndmask_b32_e64 v135, v54, 0, s[54:55]
	v_mov_b32_e32 v54, v130
	v_pk_mul_f32 v[56:57], v[140:141], v[132:133]
	v_pk_mul_f32 v[54:55], v[136:137], v[54:55]
	v_cndmask_b32_e64 v56, 0, v56, s[46:47]
	v_cndmask_b32_e64 v57, 0, v57, s[44:45]
	v_cndmask_b32_e64 v134, v134, 0, s[50:51]
	v_cndmask_b32_e64 v55, 0, v55, s[40:41]
	v_cndmask_b32_e64 v54, 0, v54, s[42:43]
	v_bfe_u32 v130, v57, 16, 1
	v_bfe_u32 v131, v56, 16, 1
	v_bfe_u32 v132, v138, 16, 1
	v_bfe_u32 v133, v135, 16, 1
	v_add3_u32 v135, v135, v133, s8
	v_add3_u32 v136, v138, v132, s8
	v_add3_u32 v131, v56, v131, s8
	v_add3_u32 v130, v57, v130, s8
	v_bfe_u32 v56, v134, 16, 1
	v_bfe_u32 v57, v129, 16, 1
	v_bfe_u32 v132, v54, 16, 1
	v_bfe_u32 v133, v55, 16, 1
	v_add3_u32 v133, v55, v133, s8
	v_add3_u32 v132, v54, v132, s8
	v_add3_u32 v129, v129, v57, s8
	v_add3_u32 v134, v134, v56, s8
	ds_read2_b64 v[54:57], v123 offset0:16 offset1:20
	v_lshrrev_b32_e32 v134, 16, v134
	v_lshrrev_b32_e32 v129, 16, v129
	v_lshrrev_b32_e32 v132, 16, v132
	v_lshrrev_b32_e32 v133, 16, v133
	v_and_or_b32 v133, v130, s9, v133
	v_and_or_b32 v132, v131, s9, v132
	v_and_or_b32 v131, v136, s9, v129
	v_and_or_b32 v130, v135, s9, v134
	s_waitcnt lgkmcnt(0)
	s_nop 0
	v_mfma_f32_16x16x32_bf16 v[46:49], v[54:57], v[130:133], v[46:49]
	ds_read2_b64 v[54:57], v128 offset0:48 offset1:52
	s_waitcnt lgkmcnt(0)
	v_mfma_f32_16x16x32_bf16 v[42:45], v[54:57], v[130:133], v[42:45]
	ds_read2_b64 v[54:57], v126 offset0:80 offset1:84
	s_waitcnt lgkmcnt(0)
	v_mfma_f32_16x16x32_bf16 v[38:41], v[54:57], v[130:133], v[38:41]
	ds_read2_b64 v[54:57], v127 offset0:112 offset1:116
	s_waitcnt lgkmcnt(0)
	v_mfma_f32_16x16x32_bf16 v[50:53], v[54:57], v[130:133], v[50:53]
	s_andn2_b64 vcc, exec, s[96:97]
	s_lshl_b32 s11, s11, 6
	s_cbranch_vccnz .LBB0_439
.LBB0_449:
	ds_read_b128 v[54:57], v122 offset:49664
	ds_read_b128 v[128:131], v122 offset:49728
	ds_read_b128 v[132:135], v122 offset:51968
	ds_read_b128 v[136:139], v122 offset:52032
	s_waitcnt lgkmcnt(3)
	v_mfma_f32_16x16x32_bf16 v[54:57], v[54:57], v[34:37], 0
	s_waitcnt lgkmcnt(1)
	v_mfma_f32_16x16x32_bf16 v[132:135], v[132:135], v[34:37], 0
	v_mfma_f32_16x16x32_bf16 v[54:57], v[128:131], v[30:33], v[54:57]
	v_mul_f32_e32 v128, v65, v106
	v_exp_f32_e32 v141, v128
	s_waitcnt lgkmcnt(0)
	v_mfma_f32_16x16x32_bf16 v[128:131], v[136:139], v[30:33], v[132:135]
	v_mul_f32_e32 v139, v65, v112
	s_nop 1
	v_mul_f32_e32 v132, v65, v107
	v_exp_f32_e32 v134, v132
	s_nop 0
	v_mul_f32_e32 v132, v65, v108
	v_exp_f32_e32 v136, v132
	v_mul_f32_e32 v132, v65, v109
	v_exp_f32_e32 v138, v132
	v_mov_b32_e32 v132, v141
	v_mul_f32_e32 v133, v65, v110
	v_exp_f32_e32 v133, v133
	v_cmp_gt_f32_e32 vcc, s1, v139
	v_mul_f32_e32 v137, v65, v111
	v_exp_f32_e32 v137, v137
	v_cndmask_b32_e32 v139, 0, v124, vcc
	v_cndmask_b32_e32 v140, 0, v119, vcc
	v_fmac_f32_e32 v140, v65, v112
	v_exp_f32_e32 v140, v140
	v_mul_f32_e32 v142, v65, v113
	v_exp_f32_e32 v142, v142
	v_mov_b32_e32 v135, v137
	v_ldexp_f32 v137, v140, v139
	v_mov_b32_e32 v139, v142
	v_mov_b32_e32 v141, v56
	v_mov_b32_e32 v56, v55
	v_mov_b32_e32 v140, v54
	v_pk_mul_f32 v[54:55], v[136:137], v[56:57]
	v_pk_mul_f32 v[132:133], v[132:133], v[140:141]
	v_cndmask_b32_e64 v136, v55, 0, s[68:69]
	v_mov_b32_e32 v55, v130
	v_mov_b32_e32 v130, v129
	v_cndmask_b32_e64 v127, v133, 0, s[64:65]
	v_cndmask_b32_e64 v133, v54, 0, s[70:71]
	v_mov_b32_e32 v54, v128
	v_pk_mul_f32 v[56:57], v[138:139], v[130:131]
	v_pk_mul_f32 v[54:55], v[134:135], v[54:55]
	v_cndmask_b32_e64 v56, 0, v56, s[62:63]
	v_cndmask_b32_e64 v57, 0, v57, s[60:61]
	v_cndmask_b32_e64 v132, v132, 0, s[66:67]
	v_cndmask_b32_e64 v55, 0, v55, s[56:57]
	v_cndmask_b32_e64 v54, 0, v54, s[58:59]
	v_bfe_u32 v128, v57, 16, 1
	v_bfe_u32 v129, v56, 16, 1
	v_bfe_u32 v130, v136, 16, 1
	v_bfe_u32 v131, v133, 16, 1
	v_add3_u32 v133, v133, v131, s8
	v_add3_u32 v134, v136, v130, s8
	v_add3_u32 v129, v56, v129, s8
	v_add3_u32 v128, v57, v128, s8
	v_bfe_u32 v56, v132, 16, 1
	v_bfe_u32 v57, v127, 16, 1
	v_bfe_u32 v130, v54, 16, 1
	v_bfe_u32 v131, v55, 16, 1
	v_add3_u32 v131, v55, v131, s8
	v_add3_u32 v130, v54, v130, s8
	v_add3_u32 v127, v127, v57, s8
	v_add3_u32 v132, v132, v56, s8
	ds_read2_b64 v[54:57], v123 offset0:24 offset1:28
	v_lshrrev_b32_e32 v132, 16, v132
	v_lshrrev_b32_e32 v127, 16, v127
	v_lshrrev_b32_e32 v130, 16, v130
	v_lshrrev_b32_e32 v131, 16, v131
	v_and_or_b32 v131, v128, s9, v131
	v_and_or_b32 v130, v129, s9, v130
	v_and_or_b32 v129, v134, s9, v127
	v_and_or_b32 v128, v133, s9, v132
	s_waitcnt lgkmcnt(0)
	s_nop 0
	v_mfma_f32_16x16x32_bf16 v[46:49], v[54:57], v[128:131], v[46:49]
	ds_read2_b64 v[54:57], v115 offset0:24 offset1:28
	s_waitcnt lgkmcnt(0)
	v_mfma_f32_16x16x32_bf16 v[42:45], v[54:57], v[128:131], v[42:45]
	ds_read2_b64 v[54:57], v126 offset0:88 offset1:92
	s_waitcnt lgkmcnt(0)
	v_mfma_f32_16x16x32_bf16 v[38:41], v[54:57], v[128:131], v[38:41]
	v_add_u32_e32 v54, 0x2000, v115
	ds_read2_b64 v[54:57], v54 offset0:88 offset1:92
	s_waitcnt lgkmcnt(0)
	v_mfma_f32_16x16x32_bf16 v[50:53], v[54:57], v[128:131], v[50:53]
	s_branch .LBB0_439
